# v46 + attention K/V LDS staging writes (ds_write_b128 of the next tile) hoisted from after the last PV MFMA group to before it, temp VGPR renamed v64->v214
# speedup vs baseline: 1.0021x; 1.0021x over previous
.LBB0_1217:
	v_lshl_add_u32 v94, s33, 14, v175
	ds_read_b64_tr_b16 v[82:83], v94 offset:0
	ds_read_b64_tr_b16 v[84:85], v94 offset:0x800
	ds_read_b64_tr_b16 v[86:87], v94 offset:0x1000
	ds_read_b64_tr_b16 v[88:89], v94 offset:0x1800
	ds_read_b64_tr_b16 v[90:91], v94 offset:0x2000
	ds_read_b64_tr_b16 v[92:93], v94 offset:0x2800
	ds_read_b64_tr_b16 v[190:191], v94 offset:0x3000
	ds_read_b64_tr_b16 v[192:193], v94 offset:0x3800
	ds_read_b64_tr_b16 v[194:195], v94 offset:0x200
	ds_read_b64_tr_b16 v[196:197], v94 offset:0xa00
	ds_read_b64_tr_b16 v[198:199], v94 offset:0x1200
	ds_read_b64_tr_b16 v[200:201], v94 offset:0x1a00
	ds_read_b64_tr_b16 v[202:203], v94 offset:0x2200
	ds_read_b64_tr_b16 v[204:205], v94 offset:0x2a00
	ds_read_b64_tr_b16 v[206:207], v94 offset:0x3200
	ds_read_b64_tr_b16 v[208:209], v94 offset:0x3a00
	s_waitcnt lgkmcnt(8)
	s_nop 0
	v_mfma_f32_32x32x16_bf16 v[48:63], v[64:67], v[82:85], v[48:63]
	v_mfma_f32_32x32x16_bf16 v[48:63], v[68:71], v[86:89], v[48:63]
	v_mfma_f32_32x32x16_bf16 v[48:63], v[72:75], v[90:93], v[48:63]
	v_mfma_f32_32x32x16_bf16 v[48:63], v[76:79], v[190:193], v[48:63]
	ds_read_b64_tr_b16 v[82:83], v94 offset:0x400
	ds_read_b64_tr_b16 v[84:85], v94 offset:0xc00
	ds_read_b64_tr_b16 v[86:87], v94 offset:0x1400
	ds_read_b64_tr_b16 v[88:89], v94 offset:0x1c00
	ds_read_b64_tr_b16 v[90:91], v94 offset:0x2400
	ds_read_b64_tr_b16 v[92:93], v94 offset:0x2c00
	ds_read_b64_tr_b16 v[190:191], v94 offset:0x3400
	ds_read_b64_tr_b16 v[192:193], v94 offset:0x3c00
	s_waitcnt lgkmcnt(8)
	v_mfma_f32_32x32x16_bf16 v[32:47], v[64:67], v[194:197], v[32:47]
	v_mfma_f32_32x32x16_bf16 v[32:47], v[68:71], v[198:201], v[32:47]
	v_mfma_f32_32x32x16_bf16 v[32:47], v[72:75], v[202:205], v[32:47]
	v_mfma_f32_32x32x16_bf16 v[32:47], v[76:79], v[206:209], v[32:47]
	ds_read_b64_tr_b16 v[194:195], v94 offset:0x600
	ds_read_b64_tr_b16 v[196:197], v94 offset:0xe00
	ds_read_b64_tr_b16 v[198:199], v94 offset:0x1600
	ds_read_b64_tr_b16 v[200:201], v94 offset:0x1e00
	ds_read_b64_tr_b16 v[202:203], v94 offset:0x2600
	ds_read_b64_tr_b16 v[204:205], v94 offset:0x2e00
	ds_read_b64_tr_b16 v[206:207], v94 offset:0x3600
	ds_read_b64_tr_b16 v[208:209], v94 offset:0x3e00
	s_waitcnt lgkmcnt(8)
	v_mfma_f32_32x32x16_bf16 v[16:31], v[64:67], v[82:85], v[16:31]
	v_mfma_f32_32x32x16_bf16 v[16:31], v[68:71], v[86:89], v[16:31]
	v_mfma_f32_32x32x16_bf16 v[16:31], v[72:75], v[90:93], v[16:31]
	v_mfma_f32_32x32x16_bf16 v[16:31], v[76:79], v[190:193], v[16:31]
	s_waitcnt lgkmcnt(0)
	s_and_b64 vcc, s[30:31], s[70:71]
	s_andn2_b64 vcc, exec, vcc
	s_cbranch_vccnz .Lattn_stage_skip
	s_mul_i32 s0, s87, 0x6400
	v_add_u32_e32 v214, s0, v173
	s_lshl_b32 s0, s77, 14
	s_waitcnt vmcnt(0)
	s_add_i32 s0, s0, 0
	s_waitcnt vmcnt(2)
	ds_write_b128 v214, v[148:151] offset:49152
	s_waitcnt vmcnt(1)
	ds_write_b128 v214, v[156:159] offset:49280
	s_waitcnt vmcnt(0)
	ds_write_b128 v214, v[160:163] offset:49408
	v_add_u32_e32 v214, s0, v170
	ds_write_b128 v214, v[144:147]
	v_add_u32_e32 v214, s0, v171
	ds_write_b128 v214, v[152:155]
.Lattn_stage_skip:
	v_mfma_f32_32x32x16_bf16 v[0:15], v[64:67], v[194:197], v[0:15]
	v_mfma_f32_32x32x16_bf16 v[0:15], v[68:71], v[198:201], v[0:15]
	v_mfma_f32_32x32x16_bf16 v[0:15], v[72:75], v[202:205], v[0:15]
	v_mfma_f32_32x32x16_bf16 v[0:15], v[76:79], v[206:209], v[0:15]
	s_andn2_b64 vcc, exec, s[30:31]
	s_cbranch_vccnz .LBB0_1221
